# prep conv stage: the per-row decay/beta section (with its cross-lane prefix chain) runs while the row loads are in flight instead of at the end of the stage
# baseline (speedup 1.0000x reference)
.LBB0_594:
	s_or_b64 exec, exec, s[0:1]
	v_lshlrev_b32_e32 v0, 2, v32
	v_lshl_add_u64 v[34:35], s[78:79], 0, v[0:1]
	s_movk_i32 s0, 0x3000
	v_add_co_u32_e32 v32, vcc, s0, v34
	s_mov_b64 s[0:1], 0x6000
	global_load_dwordx4 v[26:29], v0, s[78:79] offset:16
	global_load_dwordx4 v[38:41], v0, s[78:79]
	v_addc_co_u32_e32 v33, vcc, 0, v35, vcc
	v_lshl_add_u64 v[36:37], v[34:35], 0, s[0:1]
	s_movk_i32 s0, 0x6000
	v_sub_u32_e32 v0, 60, v168
	v_lshl_add_u64 v[30:31], v[34:35], 0, s[24:25]
	v_add_co_u32_e32 v34, vcc, s0, v34
	v_cndmask_b32_e64 v0, v0, v168, s[44:45]
	v_and_b32_e32 v150, 56, v150
	s_mov_b32 s0, 0x7ffffff8
	v_bitop3_b32 v150, v0, v150, s0 bitop3:0x6c
	v_and_b32_e32 v160, 63, v148
	s_mov_b64 s[24:25], vcc
	s_and_saveexec_b64 s[0:1], s[46:47]
	s_cbranch_execz .LBB0_598
	v_lshl_or_b32 v170, v164, 3, v163
	v_lshlrev_b32_e32 v170, 2, v170
	s_waitcnt lgkmcnt(0)
	v_mov_b32_e32 v172, s101
	s_mov_b32 s2, 0x41a00000
	s_waitcnt vmcnt(32)
	v_add_f32_e32 v172, v166, v172
	v_cmp_nlt_f32_e32 vcc, s2, v172
	s_and_saveexec_b64 s[22:23], vcc
	s_cbranch_execz .LBB0_597
	v_mul_f32_e32 v173, 0x3fb8aa3b, v172
	v_rndne_f32_e32 v174, v173
	s_mov_b32 s2, 0x3fb8aa3b
	v_sub_f32_e32 v175, v173, v174
	v_fma_f32 v173, v172, s2, -v173
	v_fmac_f32_e32 v173, 0x32a5705f, v172
	v_add_f32_e32 v173, v175, v173
	v_cvt_i32_f32_e32 v174, v174
	v_exp_f32_e32 v173, v173
	s_mov_b32 s2, 0xc2ce8ed0
	v_cmp_ngt_f32_e32 vcc, s2, v172
	s_mov_b32 s2, 0x42b17218
	v_ldexp_f32 v173, v173, v174
	v_cndmask_b32_e32 v173, 0, v173, vcc
	v_cmp_nlt_f32_e32 vcc, s2, v172
	s_mov_b32 s2, 0x3f2aaaab
	s_nop 0
	v_cndmask_b32_e32 v186, v239, v173, vcc
	v_add_f32_e32 v174, 1.0, v186
	v_add_f32_e32 v172, -1.0, v174
	v_sub_f32_e32 v173, v172, v174
	v_add_f32_e32 v173, 1.0, v173
	v_sub_f32_e32 v172, v186, v172
	v_add_f32_e32 v175, v172, v173
	v_frexp_mant_f32_e32 v176, v174
	v_cvt_f64_f32_e32 v[172:173], v174
	v_frexp_exp_i32_f64_e32 v172, v[172:173]
	v_cmp_gt_f32_e32 vcc, s2, v176
	s_mov_b32 s2, 0x3f317218
	s_nop 0
	v_subbrev_co_u32_e32 v180, vcc, 0, v172, vcc
	v_sub_u32_e32 v172, 0, v180
	v_ldexp_f32 v173, v174, v172
	v_add_f32_e32 v174, -1.0, v173
	v_add_f32_e32 v176, 1.0, v173
	v_ldexp_f32 v172, v175, v172
	v_add_f32_e32 v175, 1.0, v174
	v_add_f32_e32 v177, -1.0, v176
	v_sub_f32_e32 v175, v173, v175
	v_sub_f32_e32 v173, v173, v177
	v_add_f32_e32 v175, v172, v175
	v_add_f32_e32 v172, v172, v173
	v_add_f32_e32 v181, v176, v172
	v_rcp_f32_e32 v183, v181
	v_sub_f32_e32 v173, v176, v181
	v_add_f32_e32 v182, v172, v173
	v_add_f32_e32 v173, v174, v175
	v_mul_f32_e32 v185, v173, v183
	v_sub_f32_e32 v172, v174, v173
	v_mul_f32_e32 v174, v181, v185
	v_fma_f32 v176, v185, v181, -v174
	v_fmac_f32_e32 v176, v185, v182
	v_add_f32_e32 v184, v175, v172
	v_add_f32_e32 v172, v174, v176
	v_sub_f32_e32 v175, v173, v172
	v_pk_add_f32 v[178:179], v[172:173], v[174:175] neg_lo:[0,1] neg_hi:[0,1]
	v_mov_b32_e32 v177, v172
	v_pk_add_f32 v[172:173], v[178:179], v[176:177] neg_lo:[0,1] neg_hi:[0,1]
	s_nop 0
	v_add_f32_e32 v173, v184, v173
	v_add_f32_e32 v172, v172, v173
	v_add_f32_e32 v173, v175, v172
	v_mul_f32_e32 v184, v183, v173
	v_mul_f32_e32 v174, v181, v184
	v_fma_f32 v176, v184, v181, -v174
	v_fmac_f32_e32 v176, v184, v182
	v_sub_f32_e32 v175, v175, v173
	v_add_f32_e32 v181, v172, v175
	v_add_f32_e32 v172, v174, v176
	v_sub_f32_e32 v175, v173, v172
	v_pk_add_f32 v[178:179], v[172:173], v[174:175] neg_lo:[0,1] neg_hi:[0,1]
	v_mov_b32_e32 v177, v172
	v_pk_add_f32 v[172:173], v[178:179], v[176:177] neg_lo:[0,1] neg_hi:[0,1]
	s_nop 0
	v_add_f32_e32 v173, v181, v173
	v_add_f32_e32 v172, v172, v173
	v_add_f32_e32 v173, v185, v184
	v_add_f32_e32 v172, v175, v172
	v_sub_f32_e32 v174, v173, v185
	v_mul_f32_e32 v172, v183, v172
	v_sub_f32_e32 v174, v184, v174
	v_add_f32_e32 v174, v174, v172
	v_add_f32_e32 v176, v173, v174
	v_mul_f32_e32 v177, v176, v176
	v_fmamk_f32 v172, v177, 0x3e9b6dac, v231
	v_fmaak_f32 v203, v177, v172, 0x3f2aaada
	v_cvt_f32_i32_e32 v172, v180
	v_sub_f32_e32 v173, v176, v173
	v_sub_f32_e32 v173, v174, v173
	v_ldexp_f32 v178, v173, 1
	v_mul_f32_e32 v173, v176, v177
	v_ldexp_f32 v175, v176, 1
	v_pk_mul_f32 v[176:177], v[172:173], v[202:203]
	s_nop 0
	v_fma_f32 v174, v172, s2, -v176
	v_fmac_f32_e32 v174, 0xb102e308, v172
	v_pk_add_f32 v[172:173], v[176:177], v[174:175]
	s_mov_b32 s2, 0x7f800000
	v_sub_f32_e32 v175, v173, v175
	v_sub_f32_e32 v175, v177, v175
	v_add_f32_e32 v179, v178, v175
	v_mov_b32_e32 v178, v176
	v_pk_add_f32 v[176:177], v[172:173], v[176:177] neg_lo:[0,1] neg_hi:[0,1]
	v_pk_add_f32 v[180:181], v[172:173], v[178:179]
	v_mov_b32_e32 v175, v172
	v_mov_b32_e32 v177, v181
	v_pk_add_f32 v[182:183], v[174:175], v[176:177] neg_lo:[0,1] neg_hi:[0,1]
	v_pk_add_f32 v[174:175], v[174:175], v[176:177]
	v_mov_b32_e32 v178, v179
	v_pk_add_f32 v[176:177], v[174:175], v[172:173] op_sel:[1,0] op_sel_hi:[0,1] neg_lo:[0,1] neg_hi:[0,1]
	v_pk_add_f32 v[184:185], v[180:181], v[176:177] op_sel_hi:[1,0] neg_lo:[0,1] neg_hi:[0,1]
	v_mov_b32_e32 v180, v181
	v_mov_b32_e32 v181, v175
	v_pk_mov_b32 v[176:177], v[172:173], v[176:177] op_sel:[1,0]
	v_mov_b32_e32 v179, v172
	v_pk_add_f32 v[176:177], v[180:181], v[176:177] neg_lo:[0,1] neg_hi:[0,1]
	v_mov_b32_e32 v184, v182
	v_pk_add_f32 v[172:173], v[178:179], v[176:177] neg_lo:[0,1] neg_hi:[0,1]
	v_mov_b32_e32 v183, v175
	v_pk_add_f32 v[176:177], v[184:185], v[172:173]
	v_cmp_neq_f32_e32 vcc, s2, v186
	v_pk_add_f32 v[178:179], v[176:177], v[176:177] op_sel:[0,1] op_sel_hi:[1,0]
	s_mov_b32 s2, 0x33800000
	v_pk_add_f32 v[174:175], v[174:175], v[178:179] op_sel:[1,0] op_sel_hi:[0,1]
	v_mov_b32_e32 v177, v174
	v_pk_add_f32 v[180:181], v[176:177], v[182:183] neg_lo:[0,1] neg_hi:[0,1]
	v_mov_b32_e32 v173, v178
	v_sub_f32_e32 v175, v176, v180
	v_pk_add_f32 v[172:173], v[172:173], v[180:181] neg_lo:[0,1] neg_hi:[0,1]
	v_sub_f32_e32 v175, v182, v175
	v_add_f32_e32 v172, v172, v175
	v_add_f32_e32 v172, v172, v173
	v_add_f32_e32 v172, v174, v172
	v_cndmask_b32_e32 v172, v239, v172, vcc
	v_cmp_lt_f32_e64 vcc, |v186|, s2
	s_nop 1
	v_cndmask_b32_e32 v172, v172, v186, vcc
.LBB0_597:
	s_or_b64 exec, exec, s[22:23]
	v_mov_b32_e32 v170, s100
	v_mul_f32_e32 v165, 0xbfb8aa3b, v165
	s_mov_b32 s2, 0x3fb8aa3b
	v_exp_f32_e32 v173, v165
	s_waitcnt vmcnt(32)
	v_mul_f32_e32 v174, 0x3fb8aa3b, v170
	v_fma_f32 v175, v170, s2, -v174
	v_rndne_f32_e32 v176, v174
	v_fmac_f32_e32 v175, 0x32a5705f, v170
	v_sub_f32_e32 v174, v174, v176
	v_add_f32_e32 v174, v174, v175
	v_exp_f32_e32 v174, v174
	v_cvt_i32_f32_e32 v175, v176
	s_mov_b32 s2, 0xc2ce8ed0
	v_cmp_ngt_f32_e32 vcc, s2, v170
	s_mov_b32 s2, 0x42b17218
	v_ldexp_f32 v174, v174, v175
	v_cndmask_b32_e32 v174, 0, v174, vcc
	v_cmp_nlt_f32_e32 vcc, s2, v170
	v_and_b32_e32 v175, 64, v238
	v_add_u32_e32 v176, -1, v238
	v_cndmask_b32_e32 v170, v239, v174, vcc
	v_cmp_lt_i32_e32 vcc, v176, v175
	v_mul_f32_e64 v174, v172, -v170
	v_add_f32_e32 v173, 1.0, v173
	v_cndmask_b32_e32 v176, v176, v238, vcc
	v_lshlrev_b32_e32 v176, 2, v176
	ds_bpermute_b32 v176, v176, v174
	v_cmp_eq_u32_e32 vcc, 0, v160
	v_rcp_f32_e32 v173, v173
	s_waitcnt lgkmcnt(0)
	v_fma_f32 v170, v172, -v170, v176
	v_add_u32_e32 v172, -2, v238
	v_cndmask_b32_e32 v170, v170, v174, vcc
	v_cmp_lt_i32_e32 vcc, v172, v175
	s_nop 1
	v_cndmask_b32_e32 v172, v172, v238, vcc
	v_lshlrev_b32_e32 v172, 2, v172
	ds_bpermute_b32 v172, v172, v170
	v_cmp_gt_u32_e32 vcc, 2, v160
	s_waitcnt lgkmcnt(0)
	v_add_f32_e32 v172, v170, v172
	v_cndmask_b32_e32 v170, v172, v170, vcc
	v_add_u32_e32 v172, -4, v238
	v_cmp_lt_i32_e32 vcc, v172, v175
	s_nop 1
	v_cndmask_b32_e32 v172, v172, v238, vcc
	v_lshlrev_b32_e32 v172, 2, v172
	ds_bpermute_b32 v172, v172, v170
	v_cmp_gt_u32_e32 vcc, 4, v160
	s_waitcnt lgkmcnt(0)
	v_add_f32_e32 v172, v170, v172
	v_cndmask_b32_e32 v170, v172, v170, vcc
	v_add_u32_e32 v172, -8, v238
	v_cmp_lt_i32_e32 vcc, v172, v175
	s_nop 1
	v_cndmask_b32_e32 v172, v172, v238, vcc
	v_lshlrev_b32_e32 v172, 2, v172
	ds_bpermute_b32 v172, v172, v170
	v_cmp_gt_u32_e32 vcc, 8, v160
	s_waitcnt lgkmcnt(0)
	v_add_f32_e32 v172, v170, v172
	v_cndmask_b32_e32 v170, v172, v170, vcc
	v_add_u32_e32 v172, -16, v238
	v_cmp_lt_i32_e32 vcc, v172, v175
	s_nop 1
	v_cndmask_b32_e32 v172, v172, v238, vcc
	v_lshlrev_b32_e32 v172, 2, v172
	ds_bpermute_b32 v172, v172, v170
	v_cmp_gt_u32_e32 vcc, 16, v160
	s_waitcnt lgkmcnt(0)
	v_add_f32_e32 v172, v170, v172
	v_cndmask_b32_e32 v170, v172, v170, vcc
	v_subrev_u32_e32 v172, 32, v238
	v_cmp_lt_i32_e32 vcc, v172, v175
	s_nop 1
	v_cndmask_b32_e32 v172, v172, v238, vcc
	v_lshlrev_b32_e32 v172, 2, v172
	ds_bpermute_b32 v172, v172, v170
	v_cmp_gt_u32_e32 vcc, 32, v160
	s_waitcnt lgkmcnt(0)
	v_add_f32_e32 v172, v170, v172
	v_cndmask_b32_e32 v170, v172, v170, vcc
	v_lshl_add_u32 v172, v160, 2, v157
	ds_write_b32 v172, v173
	v_lshl_add_u32 v172, v160, 2, v157
	ds_write_b32 v172, v170 offset:256
.LBB0_598:
	s_or_b64 exec, exec, s[0:1]
	s_mov_b64 vcc, s[24:25]
	s_waitcnt vmcnt(14)
	v_lshlrev_b32_e32 v154, 16, v145
	v_and_b32_e32 v155, 0xffff0000, v145
	v_and_or_b32 v169, v0, 4, v150
	v_lshlrev_b32_e32 v150, 16, v133
	v_and_b32_e32 v151, 0xffff0000, v133
	s_waitcnt vmcnt(10)
	v_pk_mul_f32 v[152:153], v[124:125], v[154:155]
	v_lshlrev_b32_e32 v172, 16, v132
	v_pk_fma_f32 v[152:153], v[120:121], v[150:151], v[152:153]
	v_lshlrev_b32_e32 v150, 16, v141
	v_and_b32_e32 v151, 0xffff0000, v141
	s_waitcnt vmcnt(8)
	v_pk_fma_f32 v[152:153], v[128:129], v[150:151], v[152:153]
	v_and_b32_e32 v173, 0xffff0000, v132
	v_mul_f32_e32 v0, 0xbfb8aa3b, v152
	v_exp_f32_e32 v133, v0
	v_mul_f32_e32 v0, 0xbfb8aa3b, v153
	v_exp_f32_e32 v141, v0
	v_lshlrev_b32_e32 v132, 16, v144
	v_add_f32_e32 v133, 1.0, v133
	v_rcp_f32_e32 v170, v133
	v_add_f32_e32 v133, 1.0, v141
	v_rcp_f32_e32 v171, v133
	v_and_b32_e32 v133, 0xffff0000, v144
	v_lshlrev_b32_e32 v144, 16, v140
	v_and_b32_e32 v145, 0xffff0000, v140
	v_pk_mul_f32 v[140:141], v[122:123], v[132:133]
	v_lshlrev_b32_e32 v176, 16, v143
	v_pk_fma_f32 v[140:141], v[118:119], v[172:173], v[140:141]
	v_and_b32_e32 v177, 0xffff0000, v143
	v_pk_fma_f32 v[172:173], v[126:127], v[144:145], v[140:141]
	v_lshlrev_b32_e32 v174, 16, v131
	v_mul_f32_e32 v140, 0xbfb8aa3b, v172
	v_exp_f32_e32 v140, v140
	v_mul_f32_e32 v141, 0xbfb8aa3b, v173
	v_exp_f32_e32 v141, v141
	v_and_b32_e32 v175, 0xffff0000, v131
	v_add_f32_e32 v140, 1.0, v140
	v_pk_mul_f32 v[178:179], v[112:113], v[176:177]
	v_pk_mul_f32 v[170:171], v[152:153], v[170:171]
	v_rcp_f32_e32 v152, v140
	v_add_f32_e32 v153, 1.0, v141
	v_lshlrev_b32_e32 v140, 16, v139
	v_and_b32_e32 v141, 0xffff0000, v139
	v_pk_fma_f32 v[174:175], v[104:105], v[174:175], v[178:179]
	v_rcp_f32_e32 v153, v153
	v_pk_fma_f32 v[174:175], v[116:117], v[140:141], v[174:175]
	v_pk_mul_f32 v[184:185], v[124:125], v[150:151]
	v_mul_f32_e32 v131, 0xbfb8aa3b, v174
	v_exp_f32_e32 v131, v131
	v_mul_f32_e32 v139, 0xbfb8aa3b, v175
	v_exp_f32_e32 v139, v139
	v_pk_mul_f32 v[172:173], v[172:173], v[152:153]
	v_add_f32_e32 v131, 1.0, v131
	v_rcp_f32_e32 v178, v131
	v_add_f32_e32 v131, 1.0, v139
	v_rcp_f32_e32 v179, v131
	v_and_b32_e32 v131, 0xffff0000, v142
	v_lshlrev_b32_e32 v152, 16, v138
	v_and_b32_e32 v153, 0xffff0000, v138
	v_pk_mul_f32 v[174:175], v[174:175], v[178:179]
	v_lshlrev_b32_e32 v178, 16, v130
	v_and_b32_e32 v179, 0xffff0000, v130
	v_lshlrev_b32_e32 v130, 16, v142
	v_pk_mul_f32 v[138:139], v[110:111], v[130:131]
	v_pk_fma_f32 v[184:185], v[120:121], v[154:155], v[184:185]
	v_pk_fma_f32 v[138:139], v[102:103], v[178:179], v[138:139]
	v_lshlrev_b32_e32 v154, 16, v137
	v_pk_fma_f32 v[138:139], v[114:115], v[152:153], v[138:139]
	v_and_b32_e32 v155, 0xffff0000, v137
	v_mul_f32_e32 v142, 0xbfb8aa3b, v138
	v_mul_f32_e32 v143, 0xbfb8aa3b, v139
	v_exp_f32_e32 v142, v142
	v_exp_f32_e32 v143, v143
	v_pk_fma_f32 v[184:185], v[128:129], v[154:155], v[184:185]
	v_pk_mul_f32 v[192:193], v[112:113], v[140:141]
	v_mul_f32_e32 v137, 0xbfb8aa3b, v184
	v_exp_f32_e32 v137, v137
	v_mul_f32_e32 v186, 0xbfb8aa3b, v185
	v_add_f32_e32 v142, 1.0, v142
	v_add_f32_e32 v143, 1.0, v143
	v_exp_f32_e32 v187, v186
	v_rcp_f32_e32 v142, v142
	v_rcp_f32_e32 v143, v143
	v_add_f32_e32 v137, 1.0, v137
	v_rcp_f32_e32 v186, v137
	v_add_f32_e32 v137, 1.0, v187
	v_rcp_f32_e32 v187, v137
	v_pk_mul_f32 v[188:189], v[138:139], v[142:143]
	v_lshlrev_b32_e32 v142, 16, v136
	v_and_b32_e32 v143, 0xffff0000, v136
	v_pk_mul_f32 v[136:137], v[122:123], v[144:145]
	v_lshlrev_b32_e32 v138, 16, v135
	v_pk_fma_f32 v[132:133], v[118:119], v[132:133], v[136:137]
	v_and_b32_e32 v139, 0xffff0000, v135
	v_pk_fma_f32 v[132:133], v[126:127], v[142:143], v[132:133]
	v_pk_fma_f32 v[176:177], v[104:105], v[176:177], v[192:193]
	v_mul_f32_e32 v136, 0xbfb8aa3b, v132
	v_mul_f32_e32 v137, 0xbfb8aa3b, v133
	v_exp_f32_e32 v136, v136
	v_exp_f32_e32 v137, v137
	v_pk_fma_f32 v[176:177], v[116:117], v[138:139], v[176:177]
	v_pk_mul_f32 v[190:191], v[188:189], v[188:189]
	v_add_f32_e32 v136, 1.0, v136
	v_add_f32_e32 v137, 1.0, v137
	v_mul_f32_e32 v135, 0xbfb8aa3b, v176
	v_rcp_f32_e32 v136, v136
	v_rcp_f32_e32 v137, v137
	v_exp_f32_e32 v135, v135
	v_mul_f32_e32 v192, 0xbfb8aa3b, v177
	v_exp_f32_e32 v206, v192
	v_pk_mul_f32 v[192:193], v[132:133], v[136:137]
	v_add_f32_e32 v132, 1.0, v135
	v_lshlrev_b32_e32 v136, 16, v134
	v_and_b32_e32 v137, 0xffff0000, v134
	v_pk_mul_f32 v[134:135], v[110:111], v[152:153]
	v_add_f32_e32 v133, 1.0, v206
	v_pk_fma_f32 v[130:131], v[102:103], v[130:131], v[134:135]
	v_rcp_f32_e32 v132, v132
	v_pk_fma_f32 v[130:131], v[114:115], v[136:137], v[130:131]
	v_rcp_f32_e32 v133, v133
	v_mul_f32_e32 v134, 0xbfb8aa3b, v130
	v_mul_f32_e32 v135, 0xbfb8aa3b, v131
	v_exp_f32_e32 v134, v134
	v_exp_f32_e32 v135, v135
	v_pk_mul_f32 v[176:177], v[176:177], v[132:133]
	v_pk_mul_f32 v[178:179], v[174:175], v[174:175]
	v_add_f32_e32 v134, 1.0, v134
	v_add_f32_e32 v135, 1.0, v135
	v_rcp_f32_e32 v134, v134
	v_rcp_f32_e32 v135, v135
	v_pk_mul_f32 v[132:133], v[176:177], v[176:177]
	v_mov_b32_e32 v209, v190
	v_pk_mul_f32 v[182:183], v[172:173], v[172:173]
	v_pk_mul_f32 v[130:131], v[130:131], v[134:135]
	v_pk_mul_f32 v[206:207], v[192:193], v[192:193]
	v_pk_mul_f32 v[134:135], v[130:131], v[130:131]
	v_pk_mul_f32 v[184:185], v[184:185], v[186:187]
	v_mov_b32_e32 v208, v134
	v_mov_b32_e32 v190, v135
	v_pk_add_f32 v[134:135], v[208:209], v[190:191]
	v_mov_b32_e32 v190, v132
	v_mov_b32_e32 v191, v178
	v_pk_add_f32 v[134:135], v[190:191], v[134:135]
	v_mov_b32_e32 v178, v133
	v_pk_add_f32 v[132:133], v[178:179], v[134:135]
	v_mov_b32_e32 v134, v206
	v_mov_b32_e32 v135, v182
	v_pk_mul_f32 v[180:181], v[170:171], v[170:171]
	v_pk_mul_f32 v[186:187], v[184:185], v[184:185]
	v_pk_add_f32 v[132:133], v[134:135], v[132:133]
	v_mov_b32_e32 v182, v207
	v_pk_add_f32 v[132:133], v[182:183], v[132:133]
	v_mov_b32_e32 v134, v186
	v_mov_b32_e32 v135, v180
	v_pk_add_f32 v[132:133], v[134:135], v[132:133]
	v_mov_b32_e32 v180, v187
	v_pk_add_f32 v[132:133], v[180:181], v[132:133]
	s_mov_b32 s2, 0x358637bd
	v_addc_co_u32_e32 v35, vcc, 0, v35, vcc
	v_mov_b32_dpp v135, v133 quad_perm:[1,0,3,2] row_mask:0xf bank_mask:0xf bound_ctrl:1
	v_mov_b32_dpp v134, v132 quad_perm:[1,0,3,2] row_mask:0xf bank_mask:0xf bound_ctrl:1
	v_pk_add_f32 v[132:133], v[132:133], v[134:135]
	v_sub_u32_e32 v203, 63, v168
	v_lshl_add_u32 v0, v167, 1, v146
	v_mov_b32_dpp v135, v133 quad_perm:[2,3,0,1] row_mask:0xf bank_mask:0xf bound_ctrl:1
	v_mov_b32_dpp v134, v132 quad_perm:[2,3,0,1] row_mask:0xf bank_mask:0xf bound_ctrl:1
	v_pk_add_f32 v[132:133], v[132:133], v[134:135]
	global_load_dwordx4 v[42:45], v[32:33], off
	s_nop 0
	global_load_dwordx4 v[30:33], v[30:31], off offset:16
	v_mov_b32_dpp v135, v133 row_half_mirror row_mask:0xf bank_mask:0xf bound_ctrl:1
	v_mov_b32_dpp v134, v132 row_half_mirror row_mask:0xf bank_mask:0xf bound_ctrl:1
	v_pk_add_f32 v[132:133], v[132:133], v[134:135]
	global_load_dwordx4 v[46:49], v[34:35], off
	s_nop 0
	global_load_dwordx4 v[34:37], v[36:37], off offset:16
	v_mov_b32_dpp v135, v133 row_mirror row_mask:0xf bank_mask:0xf bound_ctrl:1
	v_mov_b32_dpp v134, v132 row_mirror row_mask:0xf bank_mask:0xf bound_ctrl:1
	v_pk_add_f32 v[132:133], v[132:133], v[134:135]
	v_and_b32_e32 v160, 63, v148
	v_pk_add_f32 v[134:135], v[132:133], s[2:3] op_sel_hi:[1,0]
	s_nop 0
	v_mul_f32_e32 v132, 0x4b800000, v135
	v_cmp_gt_f32_e32 vcc, s72, v135
	s_nop 1
	v_cndmask_b32_e32 v132, v135, v132, vcc
	v_rsq_f32_e32 v135, v132
	v_cndmask_b32_e64 v132, v203, v168, s[44:45]
	v_mad_u64_u32 v[132:133], s[0:1], v132, s14, v[0:1]
	v_mul_f32_e32 v133, 0x45800000, v135
	v_cndmask_b32_e32 v178, v135, v133, vcc
	v_mul_f32_e32 v133, 0x4b800000, v134
	v_cmp_gt_f32_e32 vcc, s72, v134
	v_pk_mul_f32 v[180:181], v[188:189], v[178:179] op_sel_hi:[1,0]
	v_pk_mul_f32 v[174:175], v[174:175], v[178:179] op_sel_hi:[1,0]
	v_cndmask_b32_e32 v133, v134, v133, vcc
	v_rsq_f32_e32 v133, v133
	v_pk_mul_f32 v[172:173], v[172:173], v[178:179] op_sel_hi:[1,0]
	v_pk_mul_f32 v[178:179], v[170:171], v[178:179] op_sel_hi:[1,0]
	v_cvt_pk_bf16_f32 v170, v180, v181
	v_mul_f32_e32 v134, 0x45800000, v133
	v_cvt_pk_bf16_f32 v171, v174, v175
	v_cvt_pk_bf16_f32 v172, v172, v173
	v_cvt_pk_bf16_f32 v173, v178, v179
	v_cndmask_b32_e32 v134, v133, v134, vcc
	ds_write_b128 v132, v[170:173]
	v_pk_mul_f32 v[130:131], v[130:131], v[134:135] op_sel_hi:[1,0]
	v_pk_mul_f32 v[172:173], v[176:177], v[134:135] op_sel_hi:[1,0]
	v_pk_mul_f32 v[174:175], v[192:193], v[134:135] op_sel_hi:[1,0]
	v_pk_mul_f32 v[134:135], v[184:185], v[134:135] op_sel_hi:[1,0]
	v_or_b32_e32 v133, 1, v168
	v_cvt_pk_bf16_f32 v171, v172, v173
	v_cvt_pk_bf16_f32 v173, v134, v135
	v_pk_mul_f32 v[134:135], v[124:125], v[154:155]
	v_sub_u32_e32 v170, 63, v133
	v_pk_fma_f32 v[134:135], v[120:121], v[150:151], v[134:135]
	v_lshlrev_b32_e32 v150, 16, v109
	v_and_b32_e32 v151, 0xffff0000, v109
	v_cndmask_b32_e64 v133, v170, v133, s[44:45]
	v_pk_fma_f32 v[134:135], v[128:129], v[150:151], v[134:135]
	v_pk_mul_f32 v[124:125], v[124:125], v[150:151]
	v_cvt_pk_bf16_f32 v170, v130, v131
	v_mad_u64_u32 v[130:131], s[0:1], v133, s14, v[0:1]
	v_mul_f32_e32 v109, 0xbfb8aa3b, v134
	v_pk_fma_f32 v[120:121], v[120:121], v[154:155], v[124:125]
	v_lshlrev_b32_e32 v124, 16, v101
	v_and_b32_e32 v125, 0xffff0000, v101
	v_exp_f32_e32 v109, v109
	v_mul_f32_e32 v131, 0xbfb8aa3b, v135
	v_pk_fma_f32 v[120:121], v[128:129], v[124:125], v[120:121]
	v_exp_f32_e32 v131, v131
	v_mul_f32_e32 v101, 0xbfb8aa3b, v120
	v_exp_f32_e32 v101, v101
	v_mul_f32_e32 v124, 0xbfb8aa3b, v121
	v_exp_f32_e32 v125, v124
	v_cvt_pk_bf16_f32 v172, v174, v175
	v_add_f32_e32 v109, 1.0, v109
	ds_write_b128 v130, v[170:173]
	v_rcp_f32_e32 v170, v109
	v_add_f32_e32 v109, 1.0, v131
	v_rcp_f32_e32 v171, v109
	v_lshlrev_b32_e32 v172, 16, v108
	v_and_b32_e32 v173, 0xffff0000, v108
	v_pk_mul_f32 v[108:109], v[122:123], v[142:143]
	v_add_f32_e32 v101, 1.0, v101
	v_pk_fma_f32 v[108:109], v[118:119], v[144:145], v[108:109]
	v_rcp_f32_e32 v124, v101
	v_add_f32_e32 v101, 1.0, v125
	v_pk_fma_f32 v[108:109], v[126:127], v[172:173], v[108:109]
	v_rcp_f32_e32 v125, v101
	v_mul_f32_e32 v131, 0xbfb8aa3b, v108
	v_exp_f32_e32 v131, v131
	v_mul_f32_e32 v133, 0xbfb8aa3b, v109
	v_exp_f32_e32 v133, v133
	v_pk_mul_f32 v[174:175], v[112:113], v[138:139]
	v_pk_mul_f32 v[134:135], v[134:135], v[170:171]
	v_lshlrev_b32_e32 v170, 16, v107
	v_and_b32_e32 v171, 0xffff0000, v107
	v_pk_fma_f32 v[140:141], v[104:105], v[140:141], v[174:175]
	v_pk_mul_f32 v[120:121], v[120:121], v[124:125]
	v_lshlrev_b32_e32 v124, 16, v100
	v_and_b32_e32 v125, 0xffff0000, v100
	v_pk_mul_f32 v[100:101], v[122:123], v[172:173]
	v_pk_fma_f32 v[140:141], v[116:117], v[170:171], v[140:141]
	v_pk_fma_f32 v[100:101], v[118:119], v[142:143], v[100:101]
	v_add_f32_e32 v131, 1.0, v131
	v_mul_f32_e32 v107, 0xbfb8aa3b, v140
	v_pk_fma_f32 v[100:101], v[126:127], v[124:125], v[100:101]
	v_rcp_f32_e32 v144, v131
	v_add_f32_e32 v131, 1.0, v133
	v_exp_f32_e32 v107, v107
	v_mul_f32_e32 v133, 0xbfb8aa3b, v141
	v_mul_f32_e32 v118, 0xbfb8aa3b, v100
	v_exp_f32_e32 v133, v133
	v_exp_f32_e32 v122, v118
	v_mul_f32_e32 v118, 0xbfb8aa3b, v101
	v_exp_f32_e32 v123, v118
	v_pk_mul_f32 v[112:113], v[112:113], v[170:171]
	v_lshlrev_b32_e32 v124, 16, v99
	v_and_b32_e32 v125, 0xffff0000, v99
	v_pk_fma_f32 v[104:105], v[104:105], v[138:139], v[112:113]
	v_add_f32_e32 v107, 1.0, v107
	v_pk_fma_f32 v[104:105], v[116:117], v[124:125], v[104:105]
	v_rcp_f32_e32 v174, v107
	v_add_f32_e32 v107, 1.0, v133
	v_mul_f32_e32 v99, 0xbfb8aa3b, v104
	v_rcp_f32_e32 v175, v107
	v_add_f32_e32 v122, 1.0, v122
	v_add_f32_e32 v123, 1.0, v123
	v_exp_f32_e32 v99, v99
	v_mul_f32_e32 v112, 0xbfb8aa3b, v105
	v_rcp_f32_e32 v122, v122
	v_rcp_f32_e32 v123, v123
	v_exp_f32_e32 v116, v112
	v_pk_mul_f32 v[140:141], v[140:141], v[174:175]
	v_lshlrev_b32_e32 v174, 16, v106
	v_and_b32_e32 v175, 0xffff0000, v106
	v_pk_mul_f32 v[106:107], v[110:111], v[136:137]
	v_add_f32_e32 v99, 1.0, v99
	v_pk_fma_f32 v[106:107], v[102:103], v[152:153], v[106:107]
	v_pk_mul_f32 v[112:113], v[100:101], v[122:123]
	v_rcp_f32_e32 v100, v99
	v_add_f32_e32 v101, 1.0, v116
	v_lshlrev_b32_e32 v116, 16, v98
	v_and_b32_e32 v117, 0xffff0000, v98
	v_pk_mul_f32 v[98:99], v[110:111], v[174:175]
	v_pk_fma_f32 v[106:107], v[114:115], v[174:175], v[106:107]
	v_pk_fma_f32 v[98:99], v[102:103], v[136:137], v[98:99]
	v_rcp_f32_e32 v145, v131
	v_mul_f32_e32 v131, 0xbfb8aa3b, v106
	v_pk_fma_f32 v[98:99], v[114:115], v[116:117], v[98:99]
	v_exp_f32_e32 v131, v131
	v_mul_f32_e32 v133, 0xbfb8aa3b, v107
	v_mul_f32_e32 v102, 0xbfb8aa3b, v98
	v_mul_f32_e32 v103, 0xbfb8aa3b, v99
	v_exp_f32_e32 v133, v133
	v_exp_f32_e32 v102, v102
	v_exp_f32_e32 v103, v103
	v_add_f32_e32 v131, 1.0, v131
	v_rcp_f32_e32 v178, v131
	v_add_f32_e32 v131, 1.0, v133
	v_add_f32_e32 v102, 1.0, v102
	v_add_f32_e32 v103, 1.0, v103
	v_rcp_f32_e32 v179, v131
	v_rcp_f32_e32 v102, v102
	v_rcp_f32_e32 v103, v103
	v_rcp_f32_e32 v101, v101
	v_pk_mul_f32 v[106:107], v[106:107], v[178:179]
	v_pk_mul_f32 v[152:153], v[140:141], v[140:141]
	v_pk_mul_f32 v[114:115], v[98:99], v[102:103]
	v_pk_mul_f32 v[128:129], v[106:107], v[106:107]
	v_pk_mul_f32 v[104:105], v[104:105], v[100:101]
	v_pk_mul_f32 v[98:99], v[114:115], v[114:115]
	v_pk_mul_f32 v[100:101], v[104:105], v[104:105]
	v_mov_b32_e32 v102, v98
	v_mov_b32_e32 v103, v128
	v_mov_b32_e32 v128, v99
	v_pk_mul_f32 v[108:109], v[108:109], v[144:145]
	v_pk_add_f32 v[98:99], v[102:103], v[128:129]
	v_mov_b32_e32 v102, v100
	v_mov_b32_e32 v103, v152
	v_pk_mul_f32 v[144:145], v[108:109], v[108:109]
	v_pk_mul_f32 v[110:111], v[112:113], v[112:113]
	v_pk_add_f32 v[98:99], v[102:103], v[98:99]
	v_mov_b32_e32 v152, v101
	v_pk_add_f32 v[98:99], v[152:153], v[98:99]
	v_mov_b32_e32 v100, v110
	v_mov_b32_e32 v101, v144
	v_pk_mul_f32 v[176:177], v[134:135], v[134:135]
	v_pk_mul_f32 v[118:119], v[120:121], v[120:121]
	v_pk_add_f32 v[98:99], v[100:101], v[98:99]
	v_mov_b32_e32 v144, v111
	v_pk_add_f32 v[98:99], v[144:145], v[98:99]
	v_mov_b32_e32 v100, v118
	v_mov_b32_e32 v101, v176
	v_pk_add_f32 v[98:99], v[100:101], v[98:99]
	v_mov_b32_e32 v176, v119
	v_pk_add_f32 v[98:99], v[176:177], v[98:99]
	v_or_b32_e32 v131, 2, v168
	v_sub_u32_e32 v133, 63, v131
	v_mov_b32_dpp v101, v99 quad_perm:[1,0,3,2] row_mask:0xf bank_mask:0xf bound_ctrl:1
	v_mov_b32_dpp v100, v98 quad_perm:[1,0,3,2] row_mask:0xf bank_mask:0xf bound_ctrl:1
	v_pk_add_f32 v[98:99], v[98:99], v[100:101]
	v_lshlrev_b32_e32 v118, 16, v89
	v_and_b32_e32 v119, 0xffff0000, v89
	v_mov_b32_dpp v101, v99 quad_perm:[2,3,0,1] row_mask:0xf bank_mask:0xf bound_ctrl:1
	v_mov_b32_dpp v100, v98 quad_perm:[2,3,0,1] row_mask:0xf bank_mask:0xf bound_ctrl:1
	v_pk_add_f32 v[98:99], v[98:99], v[100:101]
	s_nop 1
	v_mov_b32_dpp v101, v99 row_half_mirror row_mask:0xf bank_mask:0xf bound_ctrl:1
	v_mov_b32_dpp v100, v98 row_half_mirror row_mask:0xf bank_mask:0xf bound_ctrl:1
	v_pk_add_f32 v[98:99], v[98:99], v[100:101]
	s_nop 1
	v_mov_b32_dpp v101, v99 row_mirror row_mask:0xf bank_mask:0xf bound_ctrl:1
	v_mov_b32_dpp v100, v98 row_mirror row_mask:0xf bank_mask:0xf bound_ctrl:1
	v_pk_add_f32 v[98:99], v[98:99], v[100:101]
	s_nop 0
	v_pk_add_f32 v[100:101], v[98:99], s[2:3] op_sel_hi:[1,0]
	v_cndmask_b32_e64 v99, v133, v131, s[44:45]
	v_mul_f32_e32 v98, 0x4b800000, v101
	v_cmp_gt_f32_e32 vcc, s72, v101
	v_mad_u64_u32 v[102:103], s[0:1], v99, s14, v[0:1]
	s_nop 0
	v_cndmask_b32_e32 v98, v101, v98, vcc
	v_rsq_f32_e32 v98, v98
	v_mul_f32_e32 v101, 0x4b800000, v100
	v_and_b32_e32 v133, 0xffff0000, v54
	v_mul_f32_e32 v99, 0x45800000, v98
	v_cndmask_b32_e32 v98, v98, v99, vcc
	v_cmp_gt_f32_e32 vcc, s72, v100
	v_pk_mul_f32 v[106:107], v[106:107], v[98:99] op_sel_hi:[1,0]
	v_pk_mul_f32 v[110:111], v[140:141], v[98:99] op_sel_hi:[1,0]
	v_cndmask_b32_e32 v100, v100, v101, vcc
	v_rsq_f32_e32 v103, v100
	v_pk_mul_f32 v[108:109], v[108:109], v[98:99] op_sel_hi:[1,0]
	v_pk_mul_f32 v[116:117], v[134:135], v[98:99] op_sel_hi:[1,0]
	v_cvt_pk_bf16_f32 v98, v106, v107
	v_cvt_pk_bf16_f32 v99, v110, v111
	v_cvt_pk_bf16_f32 v100, v108, v109
	v_cvt_pk_bf16_f32 v101, v116, v117
	ds_write_b128 v102, v[98:101]
	v_mul_f32_e32 v98, 0x45800000, v103
	v_cndmask_b32_e32 v98, v103, v98, vcc
	v_pk_mul_f32 v[100:101], v[114:115], v[98:99] op_sel_hi:[1,0]
	v_pk_mul_f32 v[104:105], v[104:105], v[98:99] op_sel_hi:[1,0]
	v_pk_mul_f32 v[106:107], v[112:113], v[98:99] op_sel_hi:[1,0]
	v_pk_mul_f32 v[108:109], v[120:121], v[98:99] op_sel_hi:[1,0]
	v_or_b32_e32 v98, 3, v168
	v_sub_u32_e32 v99, 63, v98
	v_lshlrev_b32_e32 v110, 16, v97
	v_and_b32_e32 v111, 0xffff0000, v97
	v_cndmask_b32_e64 v103, v99, v98, s[44:45]
	v_cvt_pk_bf16_f32 v98, v100, v101
	v_cvt_pk_bf16_f32 v99, v104, v105
	v_lshlrev_b32_e32 v100, 16, v85
	v_and_b32_e32 v101, 0xffff0000, v85
	s_waitcnt vmcnt(8)
	v_pk_mul_f32 v[104:105], v[76:77], v[110:111]
	v_lshlrev_b32_e32 v116, 16, v84
	v_pk_fma_f32 v[100:101], v[72:73], v[100:101], v[104:105]
	v_lshlrev_b32_e32 v104, 16, v93
	v_and_b32_e32 v105, 0xffff0000, v93
	s_waitcnt vmcnt(6)
	v_pk_fma_f32 v[112:113], v[80:81], v[104:105], v[100:101]
	v_and_b32_e32 v117, 0xffff0000, v84
	v_mul_f32_e32 v85, 0xbfb8aa3b, v112
	v_exp_f32_e32 v85, v85
	v_mul_f32_e32 v93, 0xbfb8aa3b, v113
	v_exp_f32_e32 v93, v93
	v_lshlrev_b32_e32 v84, 16, v96
	v_add_f32_e32 v85, 1.0, v85
	v_rcp_f32_e32 v114, v85
	v_and_b32_e32 v85, 0xffff0000, v96
	v_cvt_pk_bf16_f32 v100, v106, v107
	v_add_f32_e32 v97, 1.0, v93
	v_lshlrev_b32_e32 v106, 16, v92
	v_and_b32_e32 v107, 0xffff0000, v92
	v_pk_mul_f32 v[92:93], v[74:75], v[84:85]
	v_rcp_f32_e32 v115, v97
	v_pk_fma_f32 v[92:93], v[70:71], v[116:117], v[92:93]
	v_lshlrev_b32_e32 v116, 16, v90
	v_pk_fma_f32 v[92:93], v[78:79], v[106:107], v[92:93]
	v_pk_mul_f32 v[120:121], v[112:113], v[114:115]
	v_mul_f32_e32 v96, 0xbfb8aa3b, v92
	v_mul_f32_e32 v101, 0xbfb8aa3b, v93
	v_exp_f32_e32 v96, v96
	v_exp_f32_e32 v101, v101
	v_lshlrev_b32_e32 v114, 16, v82
	v_and_b32_e32 v115, 0xffff0000, v82
	v_add_f32_e32 v96, 1.0, v96
	v_add_f32_e32 v97, 1.0, v101
	v_rcp_f32_e32 v96, v96
	v_rcp_f32_e32 v97, v97
	v_cvt_pk_bf16_f32 v101, v108, v109
	v_lshlrev_b32_e32 v108, 16, v91
	v_and_b32_e32 v109, 0xffff0000, v91
	v_pk_mul_f32 v[124:125], v[92:93], v[96:97]
	v_lshlrev_b32_e32 v96, 16, v95
	v_and_b32_e32 v97, 0xffff0000, v95
	v_lshlrev_b32_e32 v92, 16, v83
	v_and_b32_e32 v93, 0xffff0000, v83
	v_pk_mul_f32 v[112:113], v[64:65], v[96:97]
	v_lshlrev_b32_e32 v82, 16, v94
	v_pk_fma_f32 v[92:93], v[60:61], v[92:93], v[112:113]
	v_and_b32_e32 v117, 0xffff0000, v90
	v_pk_fma_f32 v[92:93], v[68:69], v[108:109], v[92:93]
	v_pk_mul_f32 v[136:137], v[64:65], v[108:109]
	v_mul_f32_e32 v83, 0xbfb8aa3b, v92
	v_exp_f32_e32 v83, v83
	v_mul_f32_e32 v91, 0xbfb8aa3b, v93
	v_exp_f32_e32 v91, v91
	v_pk_fma_f32 v[96:97], v[60:61], v[96:97], v[136:137]
	v_add_f32_e32 v83, 1.0, v83
	v_rcp_f32_e32 v112, v83
	v_add_f32_e32 v83, 1.0, v91
	v_rcp_f32_e32 v113, v83
	v_and_b32_e32 v83, 0xffff0000, v94
	v_pk_mul_f32 v[90:91], v[62:63], v[82:83]
	v_pk_mul_f32 v[126:127], v[124:125], v[124:125]
	v_pk_fma_f32 v[90:91], v[58:59], v[114:115], v[90:91]
	v_pk_mul_f32 v[122:123], v[120:121], v[120:121]
	v_pk_fma_f32 v[90:91], v[66:67], v[116:117], v[90:91]
	s_nop 0
	v_mul_f32_e32 v94, 0xbfb8aa3b, v90
	v_exp_f32_e32 v114, v94
	v_mul_f32_e32 v94, 0xbfb8aa3b, v91
	v_exp_f32_e32 v115, v94
	v_pk_mul_f32 v[94:95], v[92:93], v[112:113]
	v_pk_mul_f32 v[112:113], v[76:77], v[104:105]
	v_add_f32_e32 v92, 1.0, v114
	v_pk_fma_f32 v[110:111], v[72:73], v[110:111], v[112:113]
	v_add_f32_e32 v93, 1.0, v115
	v_pk_fma_f32 v[110:111], v[80:81], v[118:119], v[110:111]
	v_lshlrev_b32_e32 v114, 16, v88
	v_mul_f32_e32 v89, 0xbfb8aa3b, v110
	v_exp_f32_e32 v89, v89
	v_mul_f32_e32 v112, 0xbfb8aa3b, v111
	v_exp_f32_e32 v113, v112
	v_and_b32_e32 v115, 0xffff0000, v88
	v_add_f32_e32 v89, 1.0, v89
	v_rcp_f32_e32 v112, v89
	v_add_f32_e32 v89, 1.0, v113
	v_rcp_f32_e32 v113, v89
	v_pk_mul_f32 v[88:89], v[74:75], v[106:107]
	v_rcp_f32_e32 v92, v92
	v_pk_fma_f32 v[84:85], v[70:71], v[84:85], v[88:89]
	v_pk_mul_f32 v[134:135], v[110:111], v[112:113]
	v_pk_fma_f32 v[84:85], v[78:79], v[114:115], v[84:85]
	v_lshlrev_b32_e32 v112, 16, v87
	v_mul_f32_e32 v88, 0xbfb8aa3b, v84
	v_exp_f32_e32 v110, v88
	v_mul_f32_e32 v88, 0xbfb8aa3b, v85
	v_exp_f32_e32 v111, v88
	v_and_b32_e32 v113, 0xffff0000, v87
	v_pk_fma_f32 v[96:97], v[68:69], v[112:113], v[96:97]
	v_add_f32_e32 v110, 1.0, v110
	v_add_f32_e32 v111, 1.0, v111
	v_mul_f32_e32 v87, 0xbfb8aa3b, v96
	v_rcp_f32_e32 v110, v110
	v_rcp_f32_e32 v111, v111
	v_exp_f32_e32 v87, v87
	v_mul_f32_e32 v131, 0xbfb8aa3b, v97
	v_exp_f32_e32 v131, v131
	v_pk_mul_f32 v[136:137], v[84:85], v[110:111]
	v_add_f32_e32 v84, 1.0, v87
	v_lshlrev_b32_e32 v110, 16, v86
	v_and_b32_e32 v111, 0xffff0000, v86
	v_pk_mul_f32 v[86:87], v[62:63], v[116:117]
	v_rcp_f32_e32 v93, v93
	v_pk_fma_f32 v[82:83], v[58:59], v[82:83], v[86:87]
	v_add_f32_e32 v85, 1.0, v131
	v_pk_fma_f32 v[82:83], v[66:67], v[110:111], v[82:83]
	v_rcp_f32_e32 v84, v84
	v_mul_f32_e32 v86, 0xbfb8aa3b, v82
	v_mul_f32_e32 v87, 0xbfb8aa3b, v83
	v_exp_f32_e32 v86, v86
	v_exp_f32_e32 v87, v87
	v_rcp_f32_e32 v85, v85
	v_pk_mul_f32 v[90:91], v[90:91], v[92:93]
	v_add_f32_e32 v86, 1.0, v86
	v_add_f32_e32 v87, 1.0, v87
	v_rcp_f32_e32 v86, v86
	v_rcp_f32_e32 v87, v87
	v_pk_mul_f32 v[92:93], v[90:91], v[90:91]
	v_pk_mul_f32 v[140:141], v[96:97], v[84:85]
	v_pk_mul_f32 v[128:129], v[94:95], v[94:95]
	v_pk_mul_f32 v[86:87], v[82:83], v[86:87]
	v_pk_mul_f32 v[84:85], v[140:141], v[140:141]
	v_pk_mul_f32 v[82:83], v[86:87], v[86:87]
	v_mov_b32_e32 v97, v92
	v_mov_b32_e32 v96, v82
	v_mov_b32_e32 v92, v83
	v_pk_add_f32 v[82:83], v[96:97], v[92:93]
	v_mov_b32_e32 v92, v84
	v_mov_b32_e32 v93, v128
	v_pk_mul_f32 v[138:139], v[136:137], v[136:137]
	v_pk_add_f32 v[82:83], v[92:93], v[82:83]
	v_mov_b32_e32 v128, v85
	v_pk_add_f32 v[82:83], v[128:129], v[82:83]
	v_mov_b32_e32 v84, v138
	v_mov_b32_e32 v85, v126
	v_pk_mul_f32 v[88:89], v[134:135], v[134:135]
	v_pk_add_f32 v[82:83], v[84:85], v[82:83]
	v_mov_b32_e32 v126, v139
	v_pk_add_f32 v[82:83], v[126:127], v[82:83]
	v_mov_b32_e32 v84, v88
	v_mov_b32_e32 v85, v122
	v_pk_add_f32 v[82:83], v[84:85], v[82:83]
	v_mov_b32_e32 v122, v89
	v_pk_add_f32 v[82:83], v[122:123], v[82:83]
	v_mad_u64_u32 v[96:97], s[0:1], v103, s14, v[0:1]
	s_nop 0
	v_mov_b32_dpp v85, v83 quad_perm:[1,0,3,2] row_mask:0xf bank_mask:0xf bound_ctrl:1
	v_mov_b32_dpp v84, v82 quad_perm:[1,0,3,2] row_mask:0xf bank_mask:0xf bound_ctrl:1
	v_pk_add_f32 v[82:83], v[82:83], v[84:85]
	ds_write_b128 v96, v[98:101]
	v_pk_mul_f32 v[126:127], v[64:65], v[112:113]
	v_mov_b32_dpp v85, v83 quad_perm:[2,3,0,1] row_mask:0xf bank_mask:0xf bound_ctrl:1
	v_mov_b32_dpp v84, v82 quad_perm:[2,3,0,1] row_mask:0xf bank_mask:0xf bound_ctrl:1
	v_pk_add_f32 v[82:83], v[82:83], v[84:85]
	v_pk_fma_f32 v[108:109], v[60:61], v[108:109], v[126:127]
	s_movk_i32 s0, 0x48
	v_mov_b32_dpp v85, v83 row_half_mirror row_mask:0xf bank_mask:0xf bound_ctrl:1
	v_mov_b32_dpp v84, v82 row_half_mirror row_mask:0xf bank_mask:0xf bound_ctrl:1
	v_pk_add_f32 v[82:83], v[82:83], v[84:85]
	s_nop 1
	v_mov_b32_dpp v85, v83 row_mirror row_mask:0xf bank_mask:0xf bound_ctrl:1
	v_mov_b32_dpp v84, v82 row_mirror row_mask:0xf bank_mask:0xf bound_ctrl:1
	v_pk_add_f32 v[82:83], v[82:83], v[84:85]
	s_nop 0
	v_pk_add_f32 v[122:123], v[82:83], s[2:3] op_sel_hi:[1,0]
	s_nop 0
	v_mul_f32_e32 v82, 0x4b800000, v123
	v_cmp_gt_f32_e32 vcc, s72, v123
	s_nop 1
	v_cndmask_b32_e32 v82, v123, v82, vcc
	v_rsq_f32_e32 v82, v82
	s_nop 0
	v_mul_f32_e32 v0, 0x45800000, v82
	v_cndmask_b32_e32 v0, v82, v0, vcc
	v_pk_mul_f32 v[92:93], v[90:91], v[0:1] op_sel_hi:[1,0]
	v_pk_mul_f32 v[88:89], v[94:95], v[0:1] op_sel_hi:[1,0]
	v_pk_mul_f32 v[84:85], v[124:125], v[0:1] op_sel_hi:[1,0]
	v_pk_mul_f32 v[82:83], v[120:121], v[0:1] op_sel_hi:[1,0]
	v_mul_f32_e32 v0, 0x4b800000, v122
	v_cmp_gt_f32_e32 vcc, s72, v122
	v_cvt_pk_bf16_f32 v98, v92, v93
	v_cvt_pk_bf16_f32 v99, v88, v89
	v_cndmask_b32_e32 v0, v122, v0, vcc
	v_rsq_f32_e32 v0, v0
	v_cvt_pk_bf16_f32 v100, v84, v85
	v_cvt_pk_bf16_f32 v101, v82, v83
	ds_write_b128 v132, v[98:101] offset:17408
	v_pk_mul_f32 v[100:101], v[76:77], v[118:119]
	v_mul_f32_e32 v90, 0x45800000, v0
	v_pk_fma_f32 v[100:101], v[72:73], v[104:105], v[100:101]
	v_lshlrev_b32_e32 v120, 16, v57
	v_and_b32_e32 v121, 0xffff0000, v57
	v_cndmask_b32_e32 v0, v0, v90, vcc
	v_pk_fma_f32 v[100:101], v[80:81], v[120:121], v[100:101]
	v_pk_mul_f32 v[98:99], v[86:87], v[0:1] op_sel_hi:[1,0]
	v_pk_mul_f32 v[94:95], v[140:141], v[0:1] op_sel_hi:[1,0]
	v_pk_mul_f32 v[90:91], v[136:137], v[0:1] op_sel_hi:[1,0]
	v_pk_mul_f32 v[86:87], v[134:135], v[0:1] op_sel_hi:[1,0]
	v_mul_f32_e32 v0, 0xbfb8aa3b, v100
	v_exp_f32_e32 v0, v0
	v_mul_f32_e32 v57, 0xbfb8aa3b, v101
	v_exp_f32_e32 v57, v57
	v_lshlrev_b32_e32 v124, 16, v56
	v_add_f32_e32 v0, 1.0, v0
	v_rcp_f32_e32 v122, v0
	v_add_f32_e32 v0, 1.0, v57
	v_and_b32_e32 v125, 0xffff0000, v56
	v_pk_mul_f32 v[56:57], v[74:75], v[114:115]
	v_rcp_f32_e32 v123, v0
	v_pk_fma_f32 v[56:57], v[70:71], v[106:107], v[56:57]
	v_lshlrev_b32_e32 v132, 16, v54
	v_pk_fma_f32 v[56:57], v[78:79], v[124:125], v[56:57]
	v_pk_mul_f32 v[76:77], v[76:77], v[120:121]
	v_mul_f32_e32 v97, 0xbfb8aa3b, v56
	v_exp_f32_e32 v97, v97
	v_mul_f32_e32 v103, 0xbfb8aa3b, v57
	v_exp_f32_e32 v103, v103
	v_pk_fma_f32 v[72:73], v[72:73], v[118:119], v[76:77]
	v_add_f32_e32 v0, 1.0, v97
	v_rcp_f32_e32 v106, v0
	v_add_f32_e32 v0, 1.0, v103
	v_rcp_f32_e32 v107, v0
	v_lshlrev_b32_e32 v76, 16, v53
	v_and_b32_e32 v77, 0xffff0000, v53
	v_pk_fma_f32 v[72:73], v[80:81], v[76:77], v[72:73]
	v_pk_mul_f32 v[56:57], v[56:57], v[106:107]
	v_lshlrev_b32_e32 v106, 16, v55
	v_and_b32_e32 v107, 0xffff0000, v55
	v_pk_fma_f32 v[108:109], v[68:69], v[106:107], v[108:109]
	v_mul_f32_e32 v53, 0xbfb8aa3b, v72
	v_mul_f32_e32 v0, 0xbfb8aa3b, v108
	v_exp_f32_e32 v0, v0
	v_mul_f32_e32 v55, 0xbfb8aa3b, v109
	v_exp_f32_e32 v55, v55
	v_exp_f32_e32 v53, v53
	v_add_f32_e32 v0, 1.0, v0
	v_rcp_f32_e32 v128, v0
	v_add_f32_e32 v0, 1.0, v55
	v_pk_mul_f32 v[54:55], v[62:63], v[110:111]
	v_rcp_f32_e32 v129, v0
	v_pk_fma_f32 v[54:55], v[58:59], v[116:117], v[54:55]
	v_mul_f32_e32 v76, 0xbfb8aa3b, v73
	v_pk_fma_f32 v[54:55], v[66:67], v[132:133], v[54:55]
	v_exp_f32_e32 v77, v76
	v_mul_f32_e32 v0, 0xbfb8aa3b, v54
	v_exp_f32_e32 v0, v0
	v_mul_f32_e32 v97, 0xbfb8aa3b, v55
	v_exp_f32_e32 v97, v97
	v_pk_mul_f32 v[64:65], v[64:65], v[106:107]
	v_add_f32_e32 v0, 1.0, v0
	v_rcp_f32_e32 v116, v0
	v_add_f32_e32 v0, 1.0, v97
	v_rcp_f32_e32 v117, v0
	v_add_f32_e32 v0, 1.0, v53
	v_rcp_f32_e32 v76, v0
	v_add_f32_e32 v0, 1.0, v77
	v_rcp_f32_e32 v77, v0
	v_pk_fma_f32 v[60:61], v[60:61], v[112:113], v[64:65]
	v_pk_mul_f32 v[54:55], v[54:55], v[116:117]
	v_pk_mul_f32 v[108:109], v[108:109], v[128:129]
	v_pk_mul_f32 v[72:73], v[72:73], v[76:77]
	v_lshlrev_b32_e32 v76, 16, v52
	v_and_b32_e32 v77, 0xffff0000, v52
	v_pk_mul_f32 v[52:53], v[74:75], v[124:125]
	v_pk_mul_f32 v[116:117], v[54:55], v[54:55]
	v_pk_fma_f32 v[52:53], v[70:71], v[114:115], v[52:53]
	v_pk_mul_f32 v[80:81], v[108:109], v[108:109]
	v_pk_fma_f32 v[52:53], v[78:79], v[76:77], v[52:53]
	v_lshlrev_b32_e32 v76, 16, v51
	v_mul_f32_e32 v0, 0xbfb8aa3b, v52
	v_exp_f32_e32 v0, v0
	v_mul_f32_e32 v70, 0xbfb8aa3b, v53
	v_exp_f32_e32 v75, v70
	v_and_b32_e32 v77, 0xffff0000, v51
	v_add_f32_e32 v0, 1.0, v0
	v_rcp_f32_e32 v74, v0
	v_add_f32_e32 v0, 1.0, v75
	v_pk_fma_f32 v[60:61], v[68:69], v[76:77], v[60:61]
	v_rcp_f32_e32 v75, v0
	v_mul_f32_e32 v0, 0xbfb8aa3b, v60
	v_exp_f32_e32 v0, v0
	v_mul_f32_e32 v51, 0xbfb8aa3b, v61
	v_exp_f32_e32 v51, v51
	v_pk_mul_f32 v[64:65], v[52:53], v[74:75]
	v_add_f32_e32 v0, 1.0, v0
	v_rcp_f32_e32 v52, v0
	v_add_f32_e32 v0, 1.0, v51
	v_lshlrev_b32_e32 v68, 16, v50
	v_and_b32_e32 v69, 0xffff0000, v50
	v_pk_mul_f32 v[50:51], v[62:63], v[132:133]
	v_pk_mul_f32 v[126:127], v[56:57], v[56:57]
	v_pk_fma_f32 v[50:51], v[58:59], v[110:111], v[50:51]
	v_pk_mul_f32 v[62:63], v[64:65], v[64:65]
	v_pk_fma_f32 v[50:51], v[66:67], v[68:69], v[50:51]
	v_mov_b32_e32 v67, v116
	v_mul_f32_e32 v53, 0xbfb8aa3b, v50
	v_exp_f32_e32 v58, v53
	v_mul_f32_e32 v53, 0xbfb8aa3b, v51
	v_exp_f32_e32 v59, v53
	v_rcp_f32_e32 v53, v0
	v_add_f32_e32 v0, 1.0, v58
	v_rcp_f32_e32 v58, v0
	v_add_f32_e32 v0, 1.0, v59
	v_rcp_f32_e32 v59, v0
	v_pk_mul_f32 v[60:61], v[60:61], v[52:53]
	v_pk_mul_f32 v[100:101], v[100:101], v[122:123]
	v_pk_mul_f32 v[52:53], v[60:61], v[60:61]
	v_pk_mul_f32 v[58:59], v[50:51], v[58:59]
	v_pk_mul_f32 v[122:123], v[100:101], v[100:101]
	v_pk_mul_f32 v[50:51], v[58:59], v[58:59]
	v_pk_mul_f32 v[70:71], v[72:73], v[72:73]
	v_mov_b32_e32 v66, v50
	v_mov_b32_e32 v116, v51
	v_pk_add_f32 v[50:51], v[66:67], v[116:117]
	v_mov_b32_e32 v66, v52
	v_mov_b32_e32 v67, v80
	v_pk_add_f32 v[50:51], v[66:67], v[50:51]
	v_mov_b32_e32 v80, v53
	v_pk_add_f32 v[50:51], v[80:81], v[50:51]
	v_mov_b32_e32 v52, v62
	v_mov_b32_e32 v53, v126
	v_pk_add_f32 v[50:51], v[52:53], v[50:51]
	v_mov_b32_e32 v126, v63
	v_pk_add_f32 v[50:51], v[126:127], v[50:51]
	v_mov_b32_e32 v52, v70
	v_mov_b32_e32 v53, v122
	v_pk_add_f32 v[50:51], v[52:53], v[50:51]
	v_mov_b32_e32 v122, v71
	v_pk_add_f32 v[50:51], v[122:123], v[50:51]
	v_cvt_pk_bf16_f32 v104, v98, v99
	v_cvt_pk_bf16_f32 v105, v94, v95
	v_mov_b32_dpp v53, v51 quad_perm:[1,0,3,2] row_mask:0xf bank_mask:0xf bound_ctrl:1
	v_mov_b32_dpp v52, v50 quad_perm:[1,0,3,2] row_mask:0xf bank_mask:0xf bound_ctrl:1
	v_pk_add_f32 v[50:51], v[50:51], v[52:53]
	v_cvt_pk_bf16_f32 v106, v90, v91
	v_cvt_pk_bf16_f32 v107, v86, v87
	v_mov_b32_dpp v53, v51 quad_perm:[2,3,0,1] row_mask:0xf bank_mask:0xf bound_ctrl:1
	v_mov_b32_dpp v52, v50 quad_perm:[2,3,0,1] row_mask:0xf bank_mask:0xf bound_ctrl:1
	v_pk_add_f32 v[50:51], v[50:51], v[52:53]
	ds_write_b128 v130, v[104:107] offset:17408
	s_nop 0
	v_mov_b32_dpp v53, v51 row_half_mirror row_mask:0xf bank_mask:0xf bound_ctrl:1
	v_mov_b32_dpp v52, v50 row_half_mirror row_mask:0xf bank_mask:0xf bound_ctrl:1
	v_pk_add_f32 v[50:51], v[50:51], v[52:53]
	s_nop 1
	v_mov_b32_dpp v53, v51 row_mirror row_mask:0xf bank_mask:0xf bound_ctrl:1
	v_mov_b32_dpp v52, v50 row_mirror row_mask:0xf bank_mask:0xf bound_ctrl:1
	v_pk_add_f32 v[50:51], v[50:51], v[52:53]
	s_nop 0
	v_pk_add_f32 v[52:53], v[50:51], s[2:3] op_sel_hi:[1,0]
	s_nop 0
	v_mul_f32_e32 v0, 0x4b800000, v53
	v_cmp_gt_f32_e32 vcc, s72, v53
	s_nop 1
	v_cndmask_b32_e32 v0, v53, v0, vcc
	v_rsq_f32_e32 v0, v0
	s_nop 0
	v_mul_f32_e32 v50, 0x45800000, v0
	v_cndmask_b32_e32 v0, v0, v50, vcc
	v_pk_mul_f32 v[54:55], v[54:55], v[0:1] op_sel_hi:[1,0]
	v_pk_mul_f32 v[62:63], v[108:109], v[0:1] op_sel_hi:[1,0]
	v_pk_mul_f32 v[56:57], v[56:57], v[0:1] op_sel_hi:[1,0]
	v_pk_mul_f32 v[66:67], v[100:101], v[0:1] op_sel_hi:[1,0]
	v_mul_f32_e32 v0, 0x4b800000, v52
	v_cmp_gt_f32_e32 vcc, s72, v52
	v_cvt_pk_bf16_f32 v50, v54, v55
	v_cvt_pk_bf16_f32 v51, v62, v63
	v_cndmask_b32_e32 v0, v52, v0, vcc
	v_rsq_f32_e32 v0, v0
	v_cvt_pk_bf16_f32 v52, v56, v57
	v_cvt_pk_bf16_f32 v53, v66, v67
	ds_write_b128 v102, v[50:53] offset:17408
	v_mul_f32_e32 v50, 0x45800000, v0
	v_cndmask_b32_e32 v0, v0, v50, vcc
	v_pk_mul_f32 v[58:59], v[58:59], v[0:1] op_sel_hi:[1,0]
	v_pk_mul_f32 v[60:61], v[60:61], v[0:1] op_sel_hi:[1,0]
	v_pk_mul_f32 v[64:65], v[64:65], v[0:1] op_sel_hi:[1,0]
	v_pk_mul_f32 v[68:69], v[72:73], v[0:1] op_sel_hi:[1,0]
	v_cvt_pk_bf16_f32 v50, v58, v59
	v_cvt_pk_bf16_f32 v51, v60, v61
	v_cvt_pk_bf16_f32 v52, v64, v65
	v_cvt_pk_bf16_f32 v53, v68, v69
	ds_write_b128 v96, v[50:53] offset:17408
	v_cndmask_b32_e64 v0, v58, v92, s[44:45]
	v_cndmask_b32_e64 v50, v54, v98, s[44:45]
	v_cndmask_b32_e64 v51, v98, v54, s[44:45]
	v_cndmask_b32_e64 v52, v92, v58, s[44:45]
	v_cvt_pk_bf16_f32 v50, v0, v50
	v_mad_u32_u24 v0, v167, s0, v169
	v_cvt_pk_bf16_f32 v51, v51, v52
	v_lshl_add_u32 v0, v0, 1, v146
	v_cndmask_b32_e64 v52, v59, v93, s[44:45]
	v_cndmask_b32_e64 v53, v55, v99, s[44:45]
	v_cndmask_b32_e64 v54, v99, v55, s[44:45]
	v_cndmask_b32_e64 v55, v93, v59, s[44:45]
	v_cvt_pk_bf16_f32 v52, v52, v53
	v_cvt_pk_bf16_f32 v53, v54, v55
	v_add_u32_e32 v70, 0x8800, v0
	ds_write2_b64 v70, v[50:51], v[52:53] offset1:18
	v_cndmask_b32_e64 v50, v60, v88, s[44:45]
	v_cndmask_b32_e64 v51, v62, v94, s[44:45]
	v_cndmask_b32_e64 v52, v94, v62, s[44:45]
	v_cndmask_b32_e64 v53, v88, v60, s[44:45]
	v_cvt_pk_bf16_f32 v50, v50, v51
	v_cvt_pk_bf16_f32 v51, v52, v53
	v_cndmask_b32_e64 v52, v61, v89, s[44:45]
	v_cndmask_b32_e64 v53, v63, v95, s[44:45]
	v_cndmask_b32_e64 v54, v95, v63, s[44:45]
	v_cndmask_b32_e64 v55, v89, v61, s[44:45]
	v_cvt_pk_bf16_f32 v52, v52, v53
	v_cvt_pk_bf16_f32 v53, v54, v55
	ds_write2_b64 v70, v[50:51], v[52:53] offset0:36 offset1:54
	v_cndmask_b32_e64 v50, v64, v84, s[44:45]
	v_cndmask_b32_e64 v51, v56, v90, s[44:45]
	v_cndmask_b32_e64 v52, v90, v56, s[44:45]
	v_cndmask_b32_e64 v53, v84, v64, s[44:45]
	v_cvt_pk_bf16_f32 v50, v50, v51
	v_cvt_pk_bf16_f32 v51, v52, v53
	v_cndmask_b32_e64 v52, v65, v85, s[44:45]
	v_cndmask_b32_e64 v53, v57, v91, s[44:45]
	v_cndmask_b32_e64 v54, v91, v57, s[44:45]
	v_cndmask_b32_e64 v55, v85, v65, s[44:45]
	v_cvt_pk_bf16_f32 v52, v52, v53
	v_cvt_pk_bf16_f32 v53, v54, v55
	v_lshlrev_b32_e32 v54, 16, v10
	v_lshlrev_b32_e32 v56, 16, v6
	v_mov_b32_e32 v57, v54
	v_lshlrev_b32_e32 v55, 16, v2
	v_mov_b32_e32 v58, v56
	s_waitcnt vmcnt(3)
	v_pk_mul_f32 v[56:57], v[42:43], v[56:57] op_sel_hi:[0,1]
	ds_write2_b64 v70, v[50:51], v[52:53] offset0:72 offset1:90
	v_cndmask_b32_e64 v50, v68, v82, s[44:45]
	v_cndmask_b32_e64 v51, v66, v86, s[44:45]
	v_cndmask_b32_e64 v52, v86, v66, s[44:45]
	v_cndmask_b32_e64 v53, v82, v68, s[44:45]
	v_lshlrev_b32_e32 v59, 16, v18
	v_pk_fma_f32 v[54:55], v[38:39], v[54:55], v[56:57] op_sel_hi:[0,1,1]
	v_cvt_pk_bf16_f32 v50, v50, v51
	v_cvt_pk_bf16_f32 v51, v52, v53
	v_cndmask_b32_e64 v52, v69, v83, s[44:45]
	v_cndmask_b32_e64 v53, v67, v87, s[44:45]
	s_waitcnt vmcnt(1)
	v_pk_fma_f32 v[54:55], v[46:47], v[58:59], v[54:55] op_sel:[0,1,0] op_sel_hi:[0,0,1]
	v_cvt_pk_bf16_f32 v52, v52, v53
	v_mul_f32_e32 v53, 0xbfb8aa3b, v55
	v_exp_f32_e32 v53, v53
	v_mul_f32_e32 v56, 0xbfb8aa3b, v54
	v_exp_f32_e32 v56, v56
	v_lshlrev_b32_e32 v61, 16, v14
	v_mov_b32_e32 v60, v59
	v_add_f32_e32 v53, 1.0, v53
	v_rcp_f32_e32 v63, v53
	v_add_f32_e32 v53, 1.0, v56
	v_mov_b32_e32 v56, v61
	v_pk_mul_f32 v[60:61], v[42:43], v[60:61] op_sel_hi:[0,1]
	v_lshlrev_b32_e32 v57, 16, v22
	v_pk_fma_f32 v[58:59], v[38:39], v[58:59], v[60:61] op_sel_hi:[0,1,1]
	v_pk_fma_f32 v[56:57], v[46:47], v[56:57], v[58:59] op_sel_hi:[0,1,1]
	v_mul_f32_e32 v58, 0xbfb8aa3b, v56
	v_exp_f32_e32 v58, v58
	v_mul_f32_e32 v59, 0xbfb8aa3b, v57
	v_exp_f32_e32 v59, v59
	v_rcp_f32_e32 v62, v53
	v_add_f32_e32 v53, 1.0, v58
	v_rcp_f32_e32 v58, v53
	v_add_f32_e32 v53, 1.0, v59
	v_rcp_f32_e32 v59, v53
	v_cndmask_b32_e64 v64, v87, v67, s[44:45]
	v_cndmask_b32_e64 v65, v83, v69, s[44:45]
	v_cvt_pk_bf16_f32 v53, v64, v65
	ds_write2_b64 v70, v[50:51], v[52:53] offset0:108 offset1:126
	v_pk_mul_f32 v[50:51], v[54:55], v[62:63]
	v_pk_mul_f32 v[52:53], v[56:57], v[58:59]
	v_and_b32_e32 v55, 0xffff0000, v18
	v_cndmask_b32_e64 v61, v52, v50, s[44:45]
	v_cndmask_b32_e64 v63, v50, v52, s[44:45]
	v_and_b32_e32 v50, 0xffff0000, v10
	v_cndmask_b32_e64 v60, v53, v51, s[44:45]
	v_cndmask_b32_e64 v62, v51, v53, s[44:45]
	v_and_b32_e32 v52, 0xffff0000, v6
	v_mov_b32_e32 v53, v50
	v_and_b32_e32 v51, 0xffff0000, v2
	v_mov_b32_e32 v54, v52
	v_pk_mul_f32 v[52:53], v[42:43], v[52:53] op_sel:[1,0]
	v_and_b32_e32 v57, 0xffff0000, v14
	v_pk_fma_f32 v[50:51], v[38:39], v[50:51], v[52:53] op_sel:[1,0,0]
	v_mov_b32_e32 v56, v55
	v_pk_fma_f32 v[50:51], v[46:47], v[54:55], v[50:51] op_sel:[1,1,0] op_sel_hi:[1,0,1]
	v_pk_mul_f32 v[42:43], v[42:43], v[56:57] op_sel:[1,0]
	v_mul_f32_e32 v2, 0xbfb8aa3b, v51
	v_exp_f32_e32 v2, v2
	v_mul_f32_e32 v6, 0xbfb8aa3b, v50
	v_exp_f32_e32 v6, v6
	v_and_b32_e32 v53, 0xffff0000, v22
	v_mov_b32_e32 v52, v57
	v_pk_fma_f32 v[38:39], v[38:39], v[54:55], v[42:43] op_sel:[1,0,0]
	v_add_f32_e32 v2, 1.0, v2
	v_pk_fma_f32 v[38:39], v[46:47], v[52:53], v[38:39] op_sel:[1,0,0]
	v_rcp_f32_e32 v59, v2
	v_add_f32_e32 v2, 1.0, v6
	v_mul_f32_e32 v6, 0xbfb8aa3b, v38
	v_exp_f32_e32 v6, v6
	v_mul_f32_e32 v10, 0xbfb8aa3b, v39
	v_exp_f32_e32 v10, v10
	v_rcp_f32_e32 v58, v2
	v_add_f32_e32 v2, 1.0, v6
	v_rcp_f32_e32 v42, v2
	v_add_f32_e32 v2, 1.0, v10
	v_rcp_f32_e32 v43, v2
	v_pk_mul_f32 v[50:51], v[50:51], v[58:59]
	v_lshlrev_b32_e32 v53, 16, v19
	v_lshlrev_b32_e32 v55, 16, v15
	v_pk_mul_f32 v[38:39], v[38:39], v[42:43]
	v_lshlrev_b32_e32 v42, 16, v11
	v_cndmask_b32_e64 v2, v39, v51, s[44:45]
	v_cndmask_b32_e64 v6, v38, v50, s[44:45]
	v_cndmask_b32_e64 v10, v51, v39, s[44:45]
	v_cndmask_b32_e64 v14, v50, v38, s[44:45]
	v_lshlrev_b32_e32 v50, 16, v7
	v_mov_b32_e32 v51, v42
	v_lshlrev_b32_e32 v43, 16, v3
	v_mov_b32_e32 v52, v50
	v_pk_mul_f32 v[50:51], v[44:45], v[50:51] op_sel_hi:[0,1]
	v_pk_fma_f32 v[42:43], v[40:41], v[42:43], v[50:51] op_sel_hi:[0,1,1]
	v_pk_fma_f32 v[42:43], v[48:49], v[52:53], v[42:43] op_sel:[0,1,0] op_sel_hi:[0,0,1]
	v_cvt_pk_bf16_f32 v38, v2, v6
	v_mul_f32_e32 v2, 0xbfb8aa3b, v43
	v_exp_f32_e32 v2, v2
	v_mul_f32_e32 v6, 0xbfb8aa3b, v42
	v_exp_f32_e32 v6, v6
	v_mov_b32_e32 v54, v53
	v_mov_b32_e32 v50, v55
	v_pk_mul_f32 v[54:55], v[44:45], v[54:55] op_sel_hi:[0,1]
	v_lshlrev_b32_e32 v51, 16, v23
	v_pk_fma_f32 v[52:53], v[40:41], v[52:53], v[54:55] op_sel_hi:[0,1,1]
	v_add_f32_e32 v2, 1.0, v2
	v_pk_fma_f32 v[50:51], v[48:49], v[50:51], v[52:53] op_sel_hi:[0,1,1]
	v_rcp_f32_e32 v57, v2
	v_add_f32_e32 v2, 1.0, v6
	v_mul_f32_e32 v6, 0xbfb8aa3b, v50
	v_cvt_pk_bf16_f32 v39, v14, v10
	v_exp_f32_e32 v6, v6
	v_mul_f32_e32 v10, 0xbfb8aa3b, v51
	v_exp_f32_e32 v10, v10
	v_rcp_f32_e32 v56, v2
	v_add_f32_e32 v2, 1.0, v6
	v_rcp_f32_e32 v52, v2
	v_add_f32_e32 v2, 1.0, v10
	v_rcp_f32_e32 v53, v2
	v_and_b32_e32 v2, 0xffff0000, v11
	v_and_b32_e32 v6, 0xffff0000, v7
	v_mov_b32_e32 v7, v2
	v_mov_b32_e32 v18, v45
	v_add_u32_e32 v40, 0xd000, v0
	v_and_b32_e32 v3, 0xffff0000, v3
	v_mov_b32_e32 v10, v6
	v_mov_b32_e32 v0, v41
	v_pk_mul_f32 v[6:7], v[18:19], v[6:7] op_sel_hi:[0,1]
	v_and_b32_e32 v11, 0xffff0000, v19
	v_pk_fma_f32 v[2:3], v[0:1], v[2:3], v[6:7] op_sel_hi:[0,1,1]
	v_mov_b32_e32 v22, v49
	v_pk_fma_f32 v[2:3], v[22:23], v[10:11], v[2:3] op_sel:[0,1,0] op_sel_hi:[0,0,1]
	v_mul_f32_e32 v6, 0xbfb8aa3b, v3
	v_exp_f32_e32 v19, v6
	v_mul_f32_e32 v6, 0xbfb8aa3b, v2
	v_and_b32_e32 v7, 0xffff0000, v23
	v_exp_f32_e32 v23, v6
	v_add_f32_e32 v19, 1.0, v19
	v_rcp_f32_e32 v19, v19
	v_and_b32_e32 v15, 0xffff0000, v15
	v_mov_b32_e32 v14, v11
	v_mov_b32_e32 v6, v15
	v_pk_mul_f32 v[14:15], v[18:19], v[14:15] op_sel_hi:[0,1]
	v_add_f32_e32 v23, 1.0, v23
	v_pk_fma_f32 v[10:11], v[0:1], v[10:11], v[14:15] op_sel_hi:[0,1,1]
	v_pk_fma_f32 v[6:7], v[22:23], v[6:7], v[10:11] op_sel_hi:[0,1,1]
	v_mul_f32_e32 v0, 0xbfb8aa3b, v6
	v_exp_f32_e32 v0, v0
	v_mul_f32_e32 v10, 0xbfb8aa3b, v7
	v_exp_f32_e32 v11, v10
	v_rcp_f32_e32 v18, v23
	v_add_f32_e32 v0, 1.0, v0
	v_rcp_f32_e32 v10, v0
	v_add_f32_e32 v0, 1.0, v11
	v_rcp_f32_e32 v11, v0
	v_pk_mul_f32 v[2:3], v[2:3], v[18:19]
	v_lshlrev_b32_e32 v19, 16, v20
	v_cvt_pk_bf16_f32 v46, v60, v61
	v_pk_mul_f32 v[6:7], v[6:7], v[10:11]
	v_cvt_pk_bf16_f32 v47, v63, v62
	v_cndmask_b32_e64 v0, v7, v3, s[44:45]
	v_cndmask_b32_e64 v10, v6, v2, s[44:45]
	v_cndmask_b32_e64 v41, v2, v6, s[44:45]
	v_lshlrev_b32_e32 v6, 16, v12
	v_cvt_pk_bf16_f32 v2, v0, v10
	v_lshlrev_b32_e32 v10, 16, v8
	v_mov_b32_e32 v11, v6
	v_cndmask_b32_e64 v3, v3, v7, s[44:45]
	v_lshlrev_b32_e32 v7, 16, v4
	v_mov_b32_e32 v18, v10
	v_pk_mul_f32 v[10:11], v[30:31], v[10:11] op_sel_hi:[0,1]
	v_pk_fma_f32 v[6:7], v[26:27], v[6:7], v[10:11] op_sel_hi:[0,1,1]
	s_waitcnt vmcnt(0)
	v_pk_fma_f32 v[6:7], v[34:35], v[18:19], v[6:7] op_sel:[0,1,0] op_sel_hi:[0,0,1]
	v_mul_f32_e32 v0, 0xbfb8aa3b, v7
	v_exp_f32_e32 v0, v0
	v_mul_f32_e32 v10, 0xbfb8aa3b, v6
	v_exp_f32_e32 v10, v10
	ds_write2_b64 v40, v[46:47], v[38:39] offset1:18
	v_pk_mul_f32 v[38:39], v[42:43], v[56:57]
	v_pk_mul_f32 v[42:43], v[50:51], v[52:53]
	v_lshlrev_b32_e32 v23, 16, v16
	v_cndmask_b32_e64 v44, v43, v39, s[44:45]
	v_cndmask_b32_e64 v46, v42, v38, s[44:45]
	v_cndmask_b32_e64 v39, v39, v43, s[44:45]
	v_cndmask_b32_e64 v38, v38, v42, s[44:45]
	v_mov_b32_e32 v22, v19
	v_add_f32_e32 v0, 1.0, v0
	v_cvt_pk_bf16_f32 v15, v38, v39
	v_rcp_f32_e32 v39, v0
	v_add_f32_e32 v0, 1.0, v10
	v_mov_b32_e32 v10, v23
	v_pk_mul_f32 v[22:23], v[30:31], v[22:23] op_sel_hi:[0,1]
	v_lshlrev_b32_e32 v11, 16, v24
	v_pk_fma_f32 v[18:19], v[26:27], v[18:19], v[22:23] op_sel_hi:[0,1,1]
	v_pk_fma_f32 v[10:11], v[34:35], v[10:11], v[18:19] op_sel_hi:[0,1,1]
	v_mul_f32_e32 v18, 0xbfb8aa3b, v10
	v_exp_f32_e32 v18, v18
	v_mul_f32_e32 v19, 0xbfb8aa3b, v11
	v_exp_f32_e32 v19, v19
	v_rcp_f32_e32 v38, v0
	v_add_f32_e32 v0, 1.0, v18
	v_rcp_f32_e32 v18, v0
	v_add_f32_e32 v0, 1.0, v19
	v_rcp_f32_e32 v19, v0
	v_cvt_pk_bf16_f32 v14, v44, v46
	v_cvt_pk_bf16_f32 v3, v41, v3
	ds_write2_b64 v40, v[14:15], v[2:3] offset0:36 offset1:54
	v_pk_mul_f32 v[2:3], v[6:7], v[38:39]
	v_pk_mul_f32 v[6:7], v[10:11], v[18:19]
	v_and_b32_e32 v11, 0xffff0000, v20
	v_cndmask_b32_e64 v22, v6, v2, s[44:45]
	v_cndmask_b32_e64 v38, v2, v6, s[44:45]
	v_and_b32_e32 v2, 0xffff0000, v12
	v_cndmask_b32_e64 v0, v7, v3, s[44:45]
	v_cndmask_b32_e64 v23, v3, v7, s[44:45]
	v_and_b32_e32 v6, 0xffff0000, v8
	v_mov_b32_e32 v7, v2
	v_and_b32_e32 v3, 0xffff0000, v4
	v_mov_b32_e32 v10, v6
	v_pk_mul_f32 v[6:7], v[30:31], v[6:7] op_sel:[1,0]
	v_and_b32_e32 v15, 0xffff0000, v16
	v_pk_fma_f32 v[2:3], v[26:27], v[2:3], v[6:7] op_sel:[1,0,0]
	v_mov_b32_e32 v14, v11
	v_pk_fma_f32 v[2:3], v[34:35], v[10:11], v[2:3] op_sel:[1,1,0] op_sel_hi:[1,0,1]
	v_and_b32_e32 v7, 0xffff0000, v24
	v_mul_f32_e32 v4, 0xbfb8aa3b, v3
	v_exp_f32_e32 v4, v4
	v_mul_f32_e32 v6, 0xbfb8aa3b, v2
	v_exp_f32_e32 v8, v6
	v_mov_b32_e32 v6, v15
	v_pk_mul_f32 v[14:15], v[30:31], v[14:15] op_sel:[1,0]
	v_add_f32_e32 v4, 1.0, v4
	v_pk_fma_f32 v[10:11], v[26:27], v[10:11], v[14:15] op_sel:[1,0,0]
	v_rcp_f32_e32 v19, v4
	v_pk_fma_f32 v[6:7], v[34:35], v[6:7], v[10:11] op_sel:[1,0,0]
	v_add_f32_e32 v4, 1.0, v8
	v_mul_f32_e32 v8, 0xbfb8aa3b, v6
	v_exp_f32_e32 v8, v8
	v_mul_f32_e32 v10, 0xbfb8aa3b, v7
	v_exp_f32_e32 v11, v10
	v_rcp_f32_e32 v18, v4
	v_add_f32_e32 v4, 1.0, v8
	v_rcp_f32_e32 v10, v4
	v_add_f32_e32 v4, 1.0, v11
	v_rcp_f32_e32 v11, v4
	v_pk_mul_f32 v[2:3], v[2:3], v[18:19]
	v_cvt_pk_bf16_f32 v14, v0, v22
	v_lshlrev_b32_e32 v19, 16, v21
	v_pk_mul_f32 v[6:7], v[6:7], v[10:11]
	v_lshlrev_b32_e32 v10, 16, v9
	v_cndmask_b32_e64 v4, v6, v2, s[44:45]
	v_cndmask_b32_e64 v8, v2, v6, s[44:45]
	v_lshlrev_b32_e32 v6, 16, v13
	v_mov_b32_e32 v11, v6
	v_cndmask_b32_e64 v0, v7, v3, s[44:45]
	v_cndmask_b32_e64 v3, v3, v7, s[44:45]
	v_lshlrev_b32_e32 v7, 16, v5
	v_mov_b32_e32 v18, v10
	v_pk_mul_f32 v[10:11], v[32:33], v[10:11] op_sel_hi:[0,1]
	v_pk_fma_f32 v[6:7], v[28:29], v[6:7], v[10:11] op_sel_hi:[0,1,1]
	v_pk_fma_f32 v[6:7], v[36:37], v[18:19], v[6:7] op_sel:[0,1,0] op_sel_hi:[0,0,1]
	v_cvt_pk_bf16_f32 v2, v0, v4
	v_mul_f32_e32 v0, 0xbfb8aa3b, v7
	v_exp_f32_e32 v0, v0
	v_mul_f32_e32 v4, 0xbfb8aa3b, v6
	v_cvt_pk_bf16_f32 v15, v38, v23
	v_lshlrev_b32_e32 v23, 16, v17
	v_exp_f32_e32 v4, v4
	v_mov_b32_e32 v22, v19
	v_mov_b32_e32 v10, v23
	v_pk_mul_f32 v[22:23], v[32:33], v[22:23] op_sel_hi:[0,1]
	v_lshlrev_b32_e32 v11, 16, v25
	v_pk_fma_f32 v[18:19], v[28:29], v[18:19], v[22:23] op_sel_hi:[0,1,1]
	v_add_f32_e32 v0, 1.0, v0
	v_pk_fma_f32 v[10:11], v[36:37], v[10:11], v[18:19] op_sel_hi:[0,1,1]
	v_rcp_f32_e32 v27, v0
	v_add_f32_e32 v0, 1.0, v4
	v_mul_f32_e32 v4, 0xbfb8aa3b, v10
	v_exp_f32_e32 v4, v4
	v_mul_f32_e32 v12, 0xbfb8aa3b, v11
	v_exp_f32_e32 v12, v12
	v_rcp_f32_e32 v26, v0
	v_add_f32_e32 v0, 1.0, v4
	v_rcp_f32_e32 v18, v0
	v_add_f32_e32 v0, 1.0, v12
	v_rcp_f32_e32 v19, v0
	v_cvt_pk_bf16_f32 v3, v8, v3
	ds_write2_b64 v40, v[14:15], v[2:3] offset0:72 offset1:90
	v_pk_mul_f32 v[2:3], v[6:7], v[26:27]
	v_pk_mul_f32 v[6:7], v[10:11], v[18:19]
	v_and_b32_e32 v4, 0xffff0000, v9
	v_cndmask_b32_e64 v15, v6, v2, s[44:45]
	v_cndmask_b32_e64 v18, v2, v6, s[44:45]
	v_and_b32_e32 v2, 0xffff0000, v13
	v_cndmask_b32_e64 v14, v7, v3, s[44:45]
	v_cndmask_b32_e64 v16, v3, v7, s[44:45]
	v_and_b32_e32 v3, 0xffff0000, v5
	v_mov_b32_e32 v5, v2
	v_mov_b32_e32 v10, v33
	v_mov_b32_e32 v6, v4
	v_mov_b32_e32 v0, v29
	v_pk_mul_f32 v[4:5], v[10:11], v[4:5] op_sel_hi:[0,1]
	v_and_b32_e32 v7, 0xffff0000, v21
	v_pk_fma_f32 v[2:3], v[0:1], v[2:3], v[4:5] op_sel_hi:[0,1,1]
	v_mov_b32_e32 v12, v37
	v_pk_fma_f32 v[2:3], v[12:13], v[6:7], v[2:3] op_sel:[0,1,0] op_sel_hi:[0,0,1]
	v_mul_f32_e32 v4, 0xbfb8aa3b, v3
	v_exp_f32_e32 v11, v4
	v_mul_f32_e32 v4, 0xbfb8aa3b, v2
	v_exp_f32_e32 v13, v4
	v_and_b32_e32 v9, 0xffff0000, v17
	v_add_f32_e32 v11, 1.0, v11
	v_rcp_f32_e32 v11, v11
	v_mov_b32_e32 v8, v7
	v_mov_b32_e32 v4, v9
	v_and_b32_e32 v5, 0xffff0000, v25
	v_pk_mul_f32 v[8:9], v[10:11], v[8:9] op_sel_hi:[0,1]
	v_add_f32_e32 v13, 1.0, v13
	v_pk_fma_f32 v[6:7], v[0:1], v[6:7], v[8:9] op_sel_hi:[0,1,1]
	v_pk_fma_f32 v[4:5], v[12:13], v[4:5], v[6:7] op_sel_hi:[0,1,1]
	v_mul_f32_e32 v0, 0xbfb8aa3b, v4
	v_exp_f32_e32 v0, v0
	v_mul_f32_e32 v6, 0xbfb8aa3b, v5
	v_exp_f32_e32 v7, v6
	v_rcp_f32_e32 v10, v13
	v_add_f32_e32 v0, 1.0, v0
	v_rcp_f32_e32 v6, v0
	v_add_f32_e32 v0, 1.0, v7
	v_rcp_f32_e32 v7, v0
	v_pk_mul_f32 v[2:3], v[2:3], v[10:11]
	v_cvt_pk_bf16_f32 v8, v14, v15
	v_cvt_pk_bf16_f32 v9, v18, v16
	v_pk_mul_f32 v[4:5], v[4:5], v[6:7]
	s_nop 0
	v_cndmask_b32_e64 v0, v5, v3, s[44:45]
	v_cndmask_b32_e64 v6, v4, v2, s[44:45]
	v_cndmask_b32_e64 v3, v3, v5, s[44:45]
	v_cndmask_b32_e64 v4, v2, v4, s[44:45]
	v_cvt_pk_bf16_f32 v2, v0, v6
	v_cvt_pk_bf16_f32 v3, v4, v3
	ds_write2_b64 v40, v[8:9], v[2:3] offset0:108 offset1:126
	s_waitcnt lgkmcnt(0)
	v_readlane_b32 s0, v255, 26
	s_nop 3
	s_cmp_eq_u32 s0, 0
	s_cbranch_scc1 .Lsb_nopend
	v_readlane_b32 s22, v251, 13
	v_readlane_b32 s23, v251, 14
	s_mov_b32 s1, 0
	v_mov_b32_e32 v2, 0
	s_nop 3
